# attention units: static s_setprio 1 for waves 4-7
# speedup vs baseline: 1.0020x; 1.0005x over previous
.LBB0_1320:
	v_readfirstlane_b32 s67, v107
	s_ashr_i32 s61, s67, 6
	s_lshl_b32 s66, s61, 4
	s_and_b32 s70, s66, 48
	v_or_b32_e32 v129, s70, v109
	v_mul_u32_u24_e32 v0, s49, v129
	s_ashr_i32 s23, s67, 8
	v_lshlrev_b32_e32 v0, 1, v0
	v_lshl_add_u64 v[2:3], s[30:31], 0, v[0:1]
	s_lshl_b32 s30, s23, 6
	s_ashr_i32 s31, s30, 31
	v_mul_lo_u32 v8, s49, v120
	v_lshl_add_u64 v[2:3], s[30:31], 1, v[2:3]
	s_lshl_b32 s31, s61, 10
	s_waitcnt vmcnt(0)
	v_mul_lo_u32 v10, s0, v122
	v_mov_b32_e32 v113, v1
	v_add_lshl_u32 v0, v8, v121, 1
	s_add_i32 s76, s2, s31
	v_lshl_add_u64 v[6:7], v[2:3], 0, v[112:113]
	v_add_lshl_u32 v8, v123, v10, 1
	v_lshl_add_u64 v[10:11], s[34:35], 0, v[0:1]
	s_mov_b32 m0, s76
	v_mul_lo_u32 v9, s0, v120
	global_load_dwordx4 v[2:5], v[6:7], off
	global_load_dwordx4 v[14:17], v[6:7], off offset:64
	s_barrier
	s_add_i32 s0, s76, 0xc000
	global_load_lds_dwordx4 v0, s[34:35]
	v_lshl_add_u64 v[10:11], v[10:11], 0, s[44:45]
	s_add_i32 m0, s76, 0x2000
	v_add_lshl_u32 v6, v9, v121, 1
	global_load_lds_dwordx4 v[10:11], off
	s_mov_b32 m0, s0
	s_add_i32 s0, s59, s31
	global_load_lds_dwordx4 v6, s[36:37]
	s_add_i32 m0, s76, 0xe000
	s_lshl_b32 s74, s49, 7
	global_load_lds_dwordx4 v8, s[36:37]
	s_add_i32 m0, s76, 0x4000
	s_add_u32 s50, s34, s74
	s_addc_u32 s51, s35, 0
	v_mov_b32_e32 v7, v1
	s_waitcnt vmcnt(0)
	v_lshl_add_u64 v[18:19], s[50:51], 0, v[0:1]
	v_lshl_add_u64 v[10:11], s[36:37], 0, v[6:7]
	v_mov_b32_e32 v9, v1
	global_load_lds_dwordx4 v0, s[50:51]
	v_lshl_add_u64 v[18:19], v[18:19], 0, s[44:45]
	s_add_i32 m0, s76, 0x6000
	v_lshl_add_u64 v[12:13], s[36:37], 0, v[8:9]
	global_load_lds_dwordx4 v[18:19], off
	v_lshl_add_u64 v[18:19], v[10:11], 0, s[44:45]
	s_mov_b32 m0, s0
	s_mov_b32 s77, 1
	global_load_lds_dwordx4 v[18:19], off
	v_lshl_add_u64 v[18:19], v[12:13], 0, s[44:45]
	s_add_i32 m0, s0, 0x2000
	s_add_i32 s0, s60, s31
	global_load_lds_dwordx4 v[18:19], off
	s_add_i32 m0, s76, 0x8000
	s_add_u32 s50, s50, s74
	s_addc_u32 s51, s51, 0
	v_lshl_add_u64 v[18:19], s[50:51], 0, v[0:1]
	global_load_lds_dwordx4 v0, s[50:51]
	v_lshl_add_u64 v[18:19], v[18:19], 0, s[44:45]
	s_add_i32 m0, s76, 0xa000
	s_mov_b64 s[50:51], 0x100
	global_load_lds_dwordx4 v[18:19], off
	v_lshl_add_u64 v[10:11], v[10:11], 0, s[50:51]
	s_mov_b32 m0, s0
	s_nop 0
	global_load_lds_dwordx4 v[10:11], off
	v_lshl_add_u64 v[10:11], v[12:13], 0, s[50:51]
	s_add_i32 m0, s0, 0x2000
	s_nop 0
	global_load_lds_dwordx4 v[10:11], off
	v_lshlrev_b32_e32 v10, 16, v2
	v_and_b32_e32 v11, 0xffff0000, v2
	s_mov_b32 s0, 0x3e38aa3b
	v_lshlrev_b32_e32 v2, 16, v3
	v_and_b32_e32 v3, 0xffff0000, v3
	v_pk_mul_f32 v[10:11], v[10:11], s[0:1] op_sel_hi:[1,0]
	v_pk_mul_f32 v[2:3], v[2:3], s[0:1] op_sel_hi:[1,0]
	v_cvt_pk_bf16_f32 v10, v10, v11
	v_cvt_pk_bf16_f32 v11, v2, v3
	v_lshlrev_b32_e32 v2, 16, v4
	v_and_b32_e32 v3, 0xffff0000, v4
	v_pk_mul_f32 v[2:3], v[2:3], s[0:1] op_sel_hi:[1,0]
	s_lshl_b32 s50, s23, 13
	v_cvt_pk_bf16_f32 v12, v2, v3
	v_lshlrev_b32_e32 v2, 16, v5
	v_and_b32_e32 v3, 0xffff0000, v5
	v_pk_mul_f32 v[2:3], v[2:3], s[0:1] op_sel_hi:[1,0]
	s_waitcnt vmcnt(8)
	s_barrier
	v_cvt_pk_bf16_f32 v13, v2, v3
	v_lshlrev_b32_e32 v2, 16, v14
	v_and_b32_e32 v3, 0xffff0000, v14
	v_pk_mul_f32 v[2:3], v[2:3], s[0:1] op_sel_hi:[1,0]
	v_add_u32_e32 v34, s50, v124
	v_cvt_pk_bf16_f32 v18, v2, v3
	v_lshlrev_b32_e32 v2, 16, v15
	v_and_b32_e32 v3, 0xffff0000, v15
	v_pk_mul_f32 v[14:15], v[2:3], s[0:1] op_sel_hi:[1,0]
	ds_read_b128 v[2:5], v34
	ds_read_b128 v[22:25], v34 offset:1024
	v_cvt_pk_bf16_f32 v19, v14, v15
	v_lshlrev_b32_e32 v14, 16, v16
	v_and_b32_e32 v15, 0xffff0000, v16
	v_pk_mul_f32 v[14:15], v[14:15], s[0:1] op_sel_hi:[1,0]
	v_lshlrev_b32_e32 v26, 16, v17
	v_cvt_pk_bf16_f32 v20, v14, v15
	v_and_b32_e32 v27, 0xffff0000, v17
	s_waitcnt lgkmcnt(0)
	v_mfma_f32_16x16x32_bf16 v[2:5], v[2:5], v[10:13], 0
	ds_read_b128 v[14:17], v34 offset:2048
	v_pk_mul_f32 v[26:27], v[26:27], s[0:1] op_sel_hi:[1,0]
	ds_read_b128 v[30:33], v34 offset:6144
	v_cvt_pk_bf16_f32 v21, v26, v27
	ds_read_b128 v[26:29], v34 offset:4096
	s_waitcnt lgkmcnt(0)
	v_mfma_f32_16x16x32_bf16 v[30:33], v[30:33], v[10:13], 0
	s_add_i32 s0, s71, -2
	s_mulk_i32 s49, 0x180
	s_add_u32 s34, s34, s49
	v_mfma_f32_16x16x32_bf16 v[22:25], v[22:25], v[18:21], v[2:5]
	s_addc_u32 s35, s35, 0
	v_lshl_add_u64 v[114:115], s[34:35], 0, v[0:1]
	s_add_u32 s34, s36, 0x180
	ds_read_b128 v[2:5], v34 offset:3072
	v_mfma_f32_16x16x32_bf16 v[14:17], v[14:17], v[10:13], 0
	s_mov_b32 s88, s75
	s_mov_b32 s89, s75
	s_addc_u32 s35, s37, 0
	s_waitcnt lgkmcnt(0)
	v_mfma_f32_16x16x32_bf16 v[14:17], v[2:5], v[18:21], v[14:17]
	ds_read_b128 v[2:5], v34 offset:5120
	ds_read_b128 v[34:37], v34 offset:7168
	s_mov_b32 s90, s75
	v_mfma_f32_16x16x32_bf16 v[26:29], v[26:29], v[10:13], 0
	s_mov_b32 s91, s75
	v_lshl_add_u64 v[118:119], s[34:35], 0, v[6:7]
	v_mov_b32_e32 v6, 0
	s_waitcnt lgkmcnt(0)
	v_mfma_f32_16x16x32_bf16 v[26:29], v[2:5], v[18:21], v[26:29]
	v_mov_b64_e32 v[2:3], s[88:89]
	v_mov_b64_e32 v[4:5], s[90:91]
	v_lshl_add_u64 v[116:117], s[34:35], 0, v[8:9]
	v_mfma_f32_16x16x32_bf16 v[30:33], v[34:37], v[18:21], v[30:33]
	v_max_f32_e32 v34, v25, v25
	v_max_f32_e32 v35, v24, v24
	v_max_f32_e32 v34, v35, v34
	v_max_f32_e32 v35, v17, v17
	v_max_f32_e32 v36, v16, v16
	v_max_f32_e32 v35, v36, v35
	v_max_f32_e32 v36, v27, v27
	v_max_f32_e32 v37, v26, v26
	v_max_f32_e32 v36, v37, v36
	v_max_f32_e32 v37, v29, v29
	v_max_f32_e32 v38, v28, v28
	v_max_f32_e32 v37, v38, v37
	v_max_f32_e32 v38, v33, v33
	v_max_f32_e32 v39, v32, v32
	v_max_f32_e32 v38, v39, v38
	v_max3_f32 v38, v30, v31, v38
	v_max3_f32 v34, v22, v23, v34
	v_max3_f32 v35, v14, v15, v35
	v_max3_f32 v36, v36, v37, v38
	v_max3_f32 v34, v34, v35, v36
	v_mov_b32_e32 v35, v34
	s_nop 1
	v_permlane16_swap_b32_e32 v34, v35
	v_max_f32_e32 v35, v35, v35
	v_max_f32_e32 v34, v34, v34
	v_max_f32_e32 v34, v34, v35
	v_mov_b32_e32 v35, v34
	s_nop 1
	v_permlane32_swap_b32_e32 v34, v35
	v_max_f32_e32 v35, v35, v35
	v_max_f32_e32 v34, v34, v34
	v_max_f32_e32 v113, v34, v35
	v_sub_f32_e32 v74, v22, v113
	v_sub_f32_e32 v22, v26, v113
	v_sub_f32_e32 v26, v30, v113
	v_mov_b32_e32 v30, 0
	v_sub_f32_e32 v77, v25, v113
	v_sub_f32_e32 v76, v24, v113
	v_sub_f32_e32 v75, v23, v113
	v_sub_f32_e32 v73, v17, v113
	v_sub_f32_e32 v72, v16, v113
	v_sub_f32_e32 v71, v15, v113
	v_sub_f32_e32 v70, v14, v113
	v_sub_f32_e32 v25, v29, v113
	v_sub_f32_e32 v24, v28, v113
	v_sub_f32_e32 v23, v27, v113
	v_sub_f32_e32 v29, v33, v113
	v_sub_f32_e32 v28, v32, v113
	v_sub_f32_e32 v27, v31, v113
	v_add_u32_e32 v130, s50, v127
	s_mov_b32 s36, 0
	s_mov_b32 s37, 3
	s_mov_b32 s49, 0
	s_mov_b32 s72, 0
	s_mov_b32 s50, 0
	v_mov_b32_e32 v7, v6
	v_mov_b32_e32 v8, v6
	v_mov_b32_e32 v9, v6
	v_mov_b32_e32 v14, v6
	v_mov_b32_e32 v15, v6
	v_mov_b32_e32 v16, v6
	v_mov_b32_e32 v17, v6
	v_mov_b32_e32 v31, v30
	v_mov_b32_e32 v32, v30
	v_mov_b32_e32 v33, v30
	v_mov_b32_e32 v50, v30
	v_mov_b32_e32 v51, v30
	v_mov_b32_e32 v52, v30
	v_mov_b32_e32 v53, v30
	v_mov_b32_e32 v42, v30
	v_mov_b32_e32 v43, v30
	v_mov_b32_e32 v44, v30
	v_mov_b32_e32 v45, v30
	v_mov_b32_e32 v34, v30
	v_mov_b32_e32 v35, v30
	v_mov_b32_e32 v36, v30
	v_mov_b32_e32 v37, v30
	v_mov_b32_e32 v58, v30
	v_mov_b32_e32 v59, v30
	v_mov_b32_e32 v60, v30
	v_mov_b32_e32 v61, v30
	v_mov_b32_e32 v54, v30
	v_mov_b32_e32 v55, v30
	v_mov_b32_e32 v56, v30
	v_mov_b32_e32 v57, v30
	v_mov_b32_e32 v46, v30
	v_mov_b32_e32 v47, v30
	v_mov_b32_e32 v48, v30
	v_mov_b32_e32 v49, v30
	v_mov_b32_e32 v38, v30
	v_mov_b32_e32 v39, v30
	v_mov_b32_e32 v40, v30
	v_mov_b32_e32 v41, v30
	v_mov_b32_e32 v194, 0
	v_xor_b32_e32 v150, 0x80000000, v113
	v_mov_b32_e32 v154, s48
	v_mov_b32_e32 v151, v150
	v_mov_b32_e32 v155, v154
	v_mov_b32_e32 v152, v150
	v_mov_b32_e32 v156, v154
	v_mov_b32_e32 v153, v150
	v_mov_b32_e32 v157, v154
	v_readlane_b32 s51, v255, 8
	s_nop 3
	s_cmpk_ge_u32 s51, 0x100
	s_cbranch_scc0 .Latt_prio_skip
	s_setprio 1
.Latt_prio_skip:
	s_lshl_b32 s51, s49, 14
	v_add_u32_e32 v131, s51, v124
	ds_read_b128 v[204:207], v131 offset:49152
	ds_read_b128 v[208:211], v131 offset:51200
	ds_read_b128 v[212:215], v131 offset:53248
	ds_read_b128 v[216:219], v131 offset:55296
	s_mov_b64 s[88:89], s[86:87]
	s_cmp_ge_u32 s50, s0
	s_mov_b64 s[34:35], -1
	s_cbranch_scc0 .LBB0_1322
